# rinv table fill overlapped with the prologue DMA loads (GU, W_in); merge second-batch loads touch-prefetched alongside the first batch
# baseline (speedup 1.0000x reference)
; __device__ __forceinline__ unsigned cvt_pk_bf16(float lo, float hi) { unsigned r; asm volatile("v_cvt_pk_bf16_f32 %0, %1, %2" : "=v"(r) : "v"(lo), "v"(hi)); return r; }
; #define LAS __attribute__((address_space(3)))
; __device__ __forceinline__ int crow(int r, int hi) { return (r & 3) + 8 * (r >> 2) + 4 * hi; }
; template <bool MERGE> __device__ __forceinline__ void compute_b(LAS unsigned char* lds, const UD& x, unsigned char* ws, unsigned char* dout, int wid, int lane, const u32x4 (&pw)[10], float mx, float lsum) {
;     ...
;     asm volatile("s_waitcnt lgkmcnt(0)" ::: "memory");
; #pragma unroll
;     for (int r = 0; r < 16; ++r) {
;         const int qrow = crow(r, hi); const float rl = __builtin_amdgcn_rcpf(wsf[qrow]);
;         const unsigned a = pg8::cvt_pk_bf16(o[0][r] * rl, o[1][r] * rl);
;         stg[qrow * 64 + r32] = (bf16_t)(a & 0xffffu); stg[qrow * 64 + 32 + r32] = (bf16_t)(a >> 16);
;     }
;     asm volatile("s_waitcnt lgkmcnt(0)" ::: "memory");
;     if (!MERGE) {
;         bf16_t* Ob = o_base(ws, dout, x.br, x.b);
; #pragma unroll
;         for (int i = 0; i < 4; ++i) {
;             const int row = i * 8 + (lane >> 3), ch = lane & 7;
;             const u32x4 v = *(const LAS u32x4*)(stg + row * 64 + ch * 8);
;             *(u32x4*)(Ob + (tokb + (size_t)(t0 + row) * d + cls) * AW + x.h * HD + ch * 8) = v;
;         }
;     } else {
;         const float* ST = (const float*)(ws + WS_STAT); bf16_t* MIX = (bf16_t*)(ws + WS_MIXN);
; #pragma unroll
;         for (int i0 = 0; i0 < 4; i0 += 2) {
;             u32x4 o1[2], o2[2]; float m1[2], l1[2], m2[2], l2[2];
; #pragma unroll
;             for (int ii = 0; ii < 2; ++ii) {
;                 const int row = (i0 + ii) * 8 + (lane >> 3), ch = lane & 7; const size_t tok = tokb + (size_t)(t0 + row);
;                 const float* s1 = ST + (((size_t)1 * M + tok) * NH + x.h) * 2; const float* s2 = ST + (((size_t)2 * M + tok) * NH + x.h) * 2;
;                 m1[ii] = s1[0]; l1[ii] = s1[1]; m2[ii] = s2[0]; l2[ii] = s2[1];
;                 o1[ii] = *(const u32x4*)(o_base(ws, dout, 1, x.b) + tok * AW + x.h * HD + ch * 8); o2[ii] = *(const u32x4*)(o_base(ws, dout, 2, x.b) + tok * AW + x.h * HD + ch * 8);
;             }
.LBB0_940:
	s_or_b64 exec, exec, s[18:19]
	s_waitcnt lgkmcnt(0)
	ds_read_b32 v32, v162
	ds_read_b32 v33, v162 offset:4
	ds_read_b32 v34, v162 offset:8
	ds_read_b32 v35, v162 offset:12
	ds_read_b32 v36, v162 offset:32
	ds_read_b32 v37, v162 offset:36
	ds_read_b32 v38, v162 offset:40
	ds_read_b32 v39, v162 offset:44
	ds_read_b32 v40, v162 offset:64
	ds_read_b32 v41, v162 offset:68
	ds_read_b32 v42, v162 offset:72
	ds_read_b32 v43, v162 offset:76
	ds_read_b32 v44, v162 offset:96
	ds_read_b32 v45, v162 offset:100
	ds_read_b32 v46, v162 offset:104
	ds_read_b32 v47, v162 offset:108
	s_waitcnt lgkmcnt(0)
	s_ashr_i32 s19, s22, 31
	s_mul_i32 s24, s0, 0x500000
	v_readlane_b32 s46, v254, 59
	s_mul_hi_i32 s23, s0, 0x500000
	v_rcp_f32_e32 v32, v32
	v_readlane_b32 s47, v254, 60
	v_mov_b32_e32 v145, v81
	v_mul_f32_e32 v0, v0, v32
	v_mul_f32_e32 v16, v16, v32
	v_cvt_pk_bf16_f32 v0, v0, v16
	ds_write_b16 v163, v0
	ds_write_b16_d16_hi v164, v0
	v_rcp_f32_e32 v0, v33
	s_nop 0
	v_mul_f32_e32 v1, v1, v0
	v_mul_f32_e32 v0, v17, v0
	v_cvt_pk_bf16_f32 v0, v1, v0
	ds_write_b16 v165, v0
	ds_write_b16_d16_hi v166, v0
	v_rcp_f32_e32 v0, v34
	s_nop 0
	v_mul_f32_e32 v1, v2, v0
	v_mul_f32_e32 v0, v18, v0
	v_cvt_pk_bf16_f32 v0, v1, v0
	ds_write_b16 v167, v0
	ds_write_b16_d16_hi v168, v0
	v_rcp_f32_e32 v0, v35
	s_nop 0
	v_mul_f32_e32 v1, v3, v0
	v_mul_f32_e32 v0, v19, v0
	v_cvt_pk_bf16_f32 v0, v1, v0
	ds_write_b16 v169, v0
	ds_write_b16_d16_hi v170, v0
	v_rcp_f32_e32 v0, v36
	s_nop 0
	v_mul_f32_e32 v1, v4, v0
	v_mul_f32_e32 v0, v20, v0
	v_cvt_pk_bf16_f32 v0, v1, v0
	ds_write_b16 v171, v0
	ds_write_b16_d16_hi v172, v0
	v_rcp_f32_e32 v0, v37
	s_nop 0
	v_mul_f32_e32 v1, v5, v0
	v_mul_f32_e32 v0, v21, v0
	v_cvt_pk_bf16_f32 v0, v1, v0
	ds_write_b16 v173, v0
	ds_write_b16_d16_hi v174, v0
	v_rcp_f32_e32 v0, v38
	s_nop 0
	v_mul_f32_e32 v1, v6, v0
	v_mul_f32_e32 v0, v22, v0
	v_cvt_pk_bf16_f32 v0, v1, v0
	ds_write_b16 v175, v0
	ds_write_b16_d16_hi v176, v0
	v_rcp_f32_e32 v0, v39
	s_nop 0
	v_mul_f32_e32 v1, v7, v0
	v_mul_f32_e32 v0, v23, v0
	v_cvt_pk_bf16_f32 v0, v1, v0
	ds_write_b16 v177, v0
	ds_write_b16_d16_hi v178, v0
	v_rcp_f32_e32 v0, v40
	s_nop 0
	v_mul_f32_e32 v1, v8, v0
	v_mul_f32_e32 v0, v24, v0
	v_cvt_pk_bf16_f32 v0, v1, v0
	ds_write_b16 v179, v0
	ds_write_b16_d16_hi v180, v0
	v_rcp_f32_e32 v0, v41
	s_nop 0
	v_mul_f32_e32 v1, v9, v0
	v_mul_f32_e32 v0, v25, v0
	v_cvt_pk_bf16_f32 v0, v1, v0
	ds_write_b16 v181, v0
	ds_write_b16_d16_hi v182, v0
	v_rcp_f32_e32 v0, v42
	s_nop 0
	v_mul_f32_e32 v1, v10, v0
	v_mul_f32_e32 v0, v26, v0
	v_cvt_pk_bf16_f32 v0, v1, v0
	ds_write_b16 v183, v0
	ds_write_b16_d16_hi v184, v0
	v_rcp_f32_e32 v0, v43
	s_nop 0
	v_mul_f32_e32 v1, v11, v0
	v_mul_f32_e32 v0, v27, v0
	v_cvt_pk_bf16_f32 v0, v1, v0
	ds_write_b16 v185, v0
	ds_write_b16_d16_hi v186, v0
	v_rcp_f32_e32 v0, v44
	s_nop 0
	v_mul_f32_e32 v1, v12, v0
	v_mul_f32_e32 v0, v28, v0
	v_cvt_pk_bf16_f32 v0, v1, v0
	ds_write_b16 v187, v0
	ds_write_b16_d16_hi v188, v0
	v_rcp_f32_e32 v0, v45
	s_nop 0
	v_mul_f32_e32 v1, v13, v0
	v_mul_f32_e32 v0, v29, v0
	v_cvt_pk_bf16_f32 v0, v1, v0
	ds_write_b16 v189, v0
	ds_write_b16_d16_hi v202, v0
	v_rcp_f32_e32 v0, v46
	s_nop 0
	v_mul_f32_e32 v1, v14, v0
	v_mul_f32_e32 v0, v30, v0
	v_cvt_pk_bf16_f32 v0, v1, v0
	ds_write_b16 v203, v0
	ds_write_b16_d16_hi v204, v0
	v_or_b32_e32 v14, s20, v207
	s_add_u32 s20, s22, 0x30000
	s_addc_u32 s21, s19, 0
	s_add_u32 s18, s22, 0x60000
	v_rcp_f32_e32 v0, v47
	s_addc_u32 s19, s19, 0
	s_lshl_b64 s[16:17], s[16:17], 1
	s_add_u32 s24, s46, s24
	s_addc_u32 s23, s47, s23
	v_mul_f32_e32 v1, v15, v0
	v_mul_f32_e32 v0, v31, v0
	s_add_u32 s24, s24, s16
	v_ashrrev_i32_e32 v15, 31, v14
	v_cvt_pk_bf16_f32 v0, v1, v0
	s_addc_u32 s25, s23, s17
	v_lshl_add_u64 v[24:25], s[14:15], 0, v[14:15]
	ds_write_b16 v205, v0
	ds_write_b16_d16_hi v206, v0
	v_lshl_add_u64 v[16:17], s[24:25], 0, v[144:145]
	v_mad_u64_u32 v[0:1], s[24:25], v24, 12, s[20:21]
	v_mad_i32_i24 v1, v25, 12, v1
	v_mad_u64_u32 v[2:3], s[24:25], v24, 12, s[18:19]
	s_waitcnt lgkmcnt(0)
	v_lshl_add_u64 v[0:1], v[0:1], 3, s[34:35]
	v_mad_i32_i24 v3, v25, 12, v3
	v_lshl_add_u64 v[2:3], v[2:3], 3, s[34:35]
	global_load_dwordx2 v[34:35], v[0:1], off
	global_load_dwordx2 v[36:37], v[2:3], off
	v_lshl_add_u64 v[12:13], v[136:137], 0, s[16:17]
	v_mad_u64_u32 v[0:1], s[24:25], v24, s40, v[12:13]
	v_mad_i32_i24 v1, v25, s40, v1
	global_load_dwordx4 v[8:11], v[0:1], off
	v_mad_u64_u32 v[0:1], s[24:25], v24, s40, v[16:17]
	v_mad_i32_i24 v1, v25, s40, v1
	global_load_dwordx4 v[26:29], v[0:1], off
	v_or_b32_e32 v0, 8, v14
	v_ashrrev_i32_e32 v1, 31, v0
	v_lshl_add_u64 v[18:19], s[14:15], 0, v[0:1]
	v_mad_u64_u32 v[0:1], s[24:25], v18, 12, s[20:21]
	v_mad_i32_i24 v1, v19, 12, v1
	v_mad_u64_u32 v[2:3], s[24:25], v18, 12, s[18:19]
	v_lshl_add_u64 v[0:1], v[0:1], 3, s[34:35]
	v_mad_i32_i24 v3, v19, 12, v3
	v_lshl_add_u64 v[2:3], v[2:3], 3, s[34:35]
	global_load_dwordx2 v[20:21], v[0:1], off
	global_load_dwordx2 v[22:23], v[2:3], off
	v_mad_u64_u32 v[0:1], s[24:25], v18, s40, v[12:13]
	v_mad_i32_i24 v1, v19, s40, v1
	global_load_dwordx4 v[0:3], v[0:1], off
	v_mad_u64_u32 v[4:5], s[24:25], v18, s40, v[16:17]
	v_mad_i32_i24 v5, v19, s40, v5
	global_load_dwordx4 v[4:7], v[4:5], off
	v_or_b32_e32 v48, 16, v14
	v_ashrrev_i32_e32 v49, 31, v48
	v_lshl_add_u64 v[56:57], s[14:15], 0, v[48:49]
	v_mad_u64_u32 v[48:49], s[24:25], v56, 12, s[20:21]
	v_mad_i32_i24 v49, v57, 12, v49
	v_mad_u64_u32 v[50:51], s[24:25], v56, 12, s[18:19]
	v_lshl_add_u64 v[48:49], v[48:49], 3, s[34:35]
	v_mad_i32_i24 v51, v57, 12, v51
	v_lshl_add_u64 v[50:51], v[50:51], 3, s[34:35]
	global_load_dwordx2 v[52:53], v[48:49], off
	global_load_dwordx2 v[52:53], v[50:51], off
	v_mad_u64_u32 v[48:49], s[24:25], v56, s40, v[12:13]
	v_mad_i32_i24 v49, v57, s40, v49
	global_load_dwordx4 v[52:55], v[48:49], off
	v_mad_u64_u32 v[48:49], s[24:25], v56, s40, v[16:17]
	v_mad_i32_i24 v49, v57, s40, v49
	global_load_dwordx4 v[52:55], v[48:49], off
	v_or_b32_e32 v48, 24, v14
	v_ashrrev_i32_e32 v49, 31, v48
	v_lshl_add_u64 v[58:59], s[14:15], 0, v[48:49]
	v_mad_u64_u32 v[48:49], s[24:25], v58, 12, s[20:21]
	v_mad_i32_i24 v49, v59, 12, v49
	v_mad_u64_u32 v[50:51], s[24:25], v58, 12, s[18:19]
	v_lshl_add_u64 v[48:49], v[48:49], 3, s[34:35]
	v_mad_i32_i24 v51, v59, 12, v51
	v_lshl_add_u64 v[50:51], v[50:51], 3, s[34:35]
	global_load_dwordx2 v[52:53], v[48:49], off
	global_load_dwordx2 v[52:53], v[50:51], off
	v_mad_u64_u32 v[48:49], s[24:25], v58, s40, v[12:13]
	v_mad_i32_i24 v49, v59, s40, v49
	global_load_dwordx4 v[52:55], v[48:49], off
	v_mad_u64_u32 v[60:61], s[24:25], v58, s40, v[16:17]
	v_mad_i32_i24 v61, v59, s40, v61
	global_load_dwordx4 v[52:55], v[60:61], off
	v_add_u32_e32 v15, v208, v209
	ds_read_b128 v[30:33], v15
	ds_read2_b32 v[38:39], v210 offset1:32
	v_lshlrev_b64 v[24:25], 11, v[24:25]
	v_lshl_add_u64 v[24:25], s[84:85], 0, v[24:25]
	v_lshl_add_u64 v[24:25], v[24:25], 0, s[16:17]
	v_lshl_add_u64 v[24:25], v[24:25], 0, v[144:145]
	s_cmp_gt_i32 s22, 3
	s_waitcnt vmcnt(14) lgkmcnt(0)
; #define LAS __attribute__((address_space(3)))
; template <bool MERGE> __device__ __forceinline__ void compute_b(LAS unsigned char* lds, const UD& x, unsigned char* ws, unsigned char* dout, int wid, int lane, const u32x4 (&pw)[10], float mx, float lsum) {
;     ...
; #pragma unroll
;         for (int i0 = 0; i0 < 4; i0 += 2) {
;             u32x4 o1[2], o2[2]; float m1[2], l1[2], m2[2], l2[2];
; #pragma unroll
;             for (int ii = 0; ii < 2; ++ii) {
;                 const int row = (i0 + ii) * 8 + (lane >> 3), ch = lane & 7; const size_t tok = tokb + (size_t)(t0 + row);
;                 const float* s1 = ST + (((size_t)1 * M + tok) * NH + x.h) * 2; const float* s2 = ST + (((size_t)2 * M + tok) * NH + x.h) * 2;
;                 m1[ii] = s1[0]; l1[ii] = s1[1]; m2[ii] = s2[0]; l2[ii] = s2[1];
;                 o1[ii] = *(const u32x4*)(o_base(ws, dout, 1, x.b) + tok * AW + x.h * HD + ch * 8); o2[ii] = *(const u32x4*)(o_base(ws, dout, 2, x.b) + tok * AW + x.h * HD + ch * 8);
;             }
; #pragma unroll
;             for (int ii = 0; ii < 2; ++ii) {
;                 const int row = (i0 + ii) * 8 + (lane >> 3), ch = lane & 7; const size_t tok = tokb + (size_t)(t0 + row);
;                 const u32x4 v0 = *(const LAS u32x4*)(stg + row * 64 + ch * 8);
;                 const float m0 = wsf[32 + row], l0 = wsf[row];
;                 const float mxx = fmaxf(fmaxf(m0, m1[ii]), m2[ii]);
;                 float w0 = __builtin_amdgcn_exp2f(m0 - mxx) * l0, w1 = __builtin_amdgcn_exp2f(m1[ii] - mxx) * l1[ii], w2 = __builtin_amdgcn_exp2f(m2[ii] - mxx) * l2[ii];
;                 const float rd = 1.0f / (w0 + w1 + w2); w0 *= rd; w1 *= rd; w2 *= rd;
;                 const u32x4 a1 = o1[ii], a2 = o2[ii];
;                 u32x4 w;
;                 w.x = pg8::cvt_pk_bf16(w0 * __uint_as_float(v0.x << 16) + w1 * __uint_as_float(a1.x << 16) + w2 * __uint_as_float(a2.x << 16), w0 * __uint_as_float(v0.x & 0xffff0000u) + w1 * __uint_as_float(a1.x & 0xffff0000u) + w2 * __uint_as_float(a2.x & 0xffff0000u));
;                 w.y = pg8::cvt_pk_bf16(w0 * __uint_as_float(v0.y << 16) + w1 * __uint_as_float(a1.y << 16) + w2 * __uint_as_float(a2.y << 16), w0 * __uint_as_float(v0.y & 0xffff0000u) + w1 * __uint_as_float(a1.y & 0xffff0000u) + w2 * __uint_as_float(a2.y & 0xffff0000u));
	v_max3_f32 v15, v39, v34, v36
	v_sub_f32_e32 v39, v39, v15
	v_sub_f32_e32 v34, v34, v15
	v_sub_f32_e32 v15, v36, v15
	v_exp_f32_e32 v41, v39
	v_exp_f32_e32 v40, v15
	v_exp_f32_e32 v34, v34
	s_waitcnt vmcnt(13)
	v_lshlrev_b32_e32 v15, 16, v8
	v_and_b32_e32 v36, 0xffff0000, v8
	v_lshlrev_b32_e32 v42, 16, v9
	v_and_b32_e32 v43, 0xffff0000, v9
	v_mov_b32_e32 v8, v37
	v_mov_b32_e32 v9, v38
	v_pk_mul_f32 v[8:9], v[8:9], v[40:41]
	v_lshlrev_b32_e32 v44, 16, v10
	v_and_b32_e32 v45, 0xffff0000, v10
	v_fma_f32 v10, v35, v34, v9
	v_add_f32_e32 v10, v8, v10
	v_mul_f32_e32 v39, v35, v34
	v_div_scale_f32 v34, s[24:25], v10, v10, 1.0
	v_rcp_f32_e32 v35, v34
	v_lshlrev_b32_e32 v46, 16, v11
	v_fma_f32 v37, -v34, v35, 1.0
	v_fmac_f32_e32 v35, v37, v35
	v_div_scale_f32 v37, vcc, 1.0, v10, 1.0
	v_mul_f32_e32 v38, v37, v35
	v_fma_f32 v40, -v34, v38, v37
	v_fmac_f32_e32 v38, v40, v35
	v_fma_f32 v34, -v34, v38, v37
	v_div_fmas_f32 v34, v34, v35, v38
	v_div_fixup_f32 v10, v34, v10, 1.0
	v_pk_mul_f32 v[34:35], v[8:9], v[10:11] op_sel_hi:[1,0]
	s_waitcnt vmcnt(12)
	v_lshlrev_b32_e32 v8, 16, v26
	v_lshlrev_b32_e32 v9, 16, v30
	v_mul_f32_e32 v38, v39, v10
	v_pk_mul_f32 v[8:9], v[34:35], v[8:9]
	v_lshlrev_b32_e32 v37, 16, v31
	v_fma_f32 v9, v38, v15, v9
	v_add_f32_e32 v10, v8, v9
	v_and_b32_e32 v9, 0xffff0000, v30
	v_and_b32_e32 v8, 0xffff0000, v26
	v_pk_mul_f32 v[8:9], v[34:35], v[8:9]
	v_and_b32_e32 v31, 0xffff0000, v31
	v_fma_f32 v9, v38, v36, v9
	v_and_b32_e32 v30, 0xffff0000, v27
	v_add_f32_e32 v8, v8, v9
	v_lshlrev_b32_e32 v36, 16, v27
	v_pk_mul_f32 v[26:27], v[34:35], v[30:31]
	v_cvt_pk_bf16_f32 v8, v10, v8
	v_pk_mul_f32 v[36:37], v[34:35], v[36:37]
	v_fma_f32 v10, v38, v43, v27
	v_fma_f32 v9, v38, v42, v37
	v_add_f32_e32 v10, v26, v10
	v_lshlrev_b32_e32 v26, 16, v28
	v_lshlrev_b32_e32 v27, 16, v32
	v_add_f32_e32 v9, v36, v9
	v_pk_mul_f32 v[26:27], v[34:35], v[26:27]
	v_cvt_pk_bf16_f32 v9, v9, v10
	v_and_b32_e32 v11, 0xffff0000, v11
	v_fma_f32 v10, v38, v44, v27
	v_add_f32_e32 v10, v26, v10
	v_and_b32_e32 v27, 0xffff0000, v32
	v_and_b32_e32 v26, 0xffff0000, v28
	v_pk_mul_f32 v[26:27], v[34:35], v[26:27]
	s_waitcnt vmcnt(9)
	v_lshlrev_b32_e32 v28, 16, v1
	v_fma_f32 v15, v38, v45, v27
	v_add_f32_e32 v15, v26, v15
	v_lshlrev_b32_e32 v26, 16, v29
	v_lshlrev_b32_e32 v27, 16, v33
	v_pk_mul_f32 v[26:27], v[34:35], v[26:27]
	v_cvt_pk_bf16_f32 v10, v10, v15
	v_lshlrev_b32_e32 v30, 16, v2
	v_fma_f32 v15, v38, v46, v27
	v_add_f32_e32 v15, v26, v15
	v_and_b32_e32 v27, 0xffff0000, v33
	v_and_b32_e32 v26, 0xffff0000, v29
	v_pk_mul_f32 v[26:27], v[34:35], v[26:27]
	v_and_b32_e32 v29, 0xffff0000, v1
	v_fma_f32 v11, v38, v11, v27
	v_add_f32_e32 v11, v26, v11
	v_cvt_pk_bf16_f32 v11, v15, v11
	global_store_dwordx4 v[24:25], v[8:11], off offset:512
	ds_read_b128 v[8:11], v229
	ds_read2_b32 v[26:27], v210 offset0:8 offset1:40
	v_and_b32_e32 v31, 0xffff0000, v2
	v_lshlrev_b32_e32 v32, 16, v3
	s_waitcnt lgkmcnt(0)
	v_max3_f32 v15, v27, v20, v22
	v_sub_f32_e32 v24, v27, v15
	v_sub_f32_e32 v20, v20, v15
	v_sub_f32_e32 v15, v22, v15
	v_exp_f32_e32 v25, v24
	v_exp_f32_e32 v24, v15
	v_exp_f32_e32 v20, v20
	v_lshlrev_b32_e32 v15, 16, v0
	v_and_b32_e32 v22, 0xffff0000, v0
	v_mov_b32_e32 v0, v23
	v_mov_b32_e32 v1, v26
	v_pk_mul_f32 v[0:1], v[0:1], v[24:25]
	v_mul_f32_e32 v27, v21, v20
	v_fma_f32 v2, v21, v20, v1
	v_add_f32_e32 v2, v0, v2
	v_div_scale_f32 v20, s[24:25], v2, v2, 1.0
	v_rcp_f32_e32 v21, v20
	s_nop 0
	v_fma_f32 v23, -v20, v21, 1.0
	v_fmac_f32_e32 v21, v23, v21
	v_div_scale_f32 v23, vcc, 1.0, v2, 1.0
	v_mul_f32_e32 v24, v23, v21
	v_fma_f32 v25, -v20, v24, v23
	v_fmac_f32_e32 v24, v25, v21
	v_fma_f32 v20, -v20, v24, v23
	v_div_fmas_f32 v20, v20, v21, v24
	v_div_fixup_f32 v2, v20, v2, 1.0
	v_pk_mul_f32 v[20:21], v[0:1], v[2:3] op_sel_hi:[1,0]
	s_waitcnt vmcnt(9)
	v_lshlrev_b32_e32 v0, 16, v4
	v_lshlrev_b32_e32 v1, 16, v8
	v_mul_f32_e32 v24, v27, v2
	v_pk_mul_f32 v[0:1], v[20:21], v[0:1]
	v_lshlrev_b32_e32 v23, 16, v9
	v_fma_f32 v1, v24, v15, v1
	v_add_f32_e32 v2, v0, v1
	v_and_b32_e32 v1, 0xffff0000, v8
	v_and_b32_e32 v0, 0xffff0000, v4
	v_pk_mul_f32 v[0:1], v[20:21], v[0:1]
	v_and_b32_e32 v9, 0xffff0000, v9
	v_fma_f32 v1, v24, v22, v1
	v_and_b32_e32 v8, 0xffff0000, v5
	v_add_f32_e32 v0, v0, v1
	v_lshlrev_b32_e32 v22, 16, v5
	v_pk_mul_f32 v[4:5], v[20:21], v[8:9]
	v_cvt_pk_bf16_f32 v0, v2, v0
	v_pk_mul_f32 v[22:23], v[20:21], v[22:23]
	v_fma_f32 v2, v24, v29, v5
	v_fma_f32 v1, v24, v28, v23
	v_add_f32_e32 v2, v4, v2
	v_lshlrev_b32_e32 v4, 16, v6
	v_lshlrev_b32_e32 v5, 16, v10
	v_add_f32_e32 v1, v22, v1
	v_pk_mul_f32 v[4:5], v[20:21], v[4:5]
	v_cvt_pk_bf16_f32 v1, v1, v2
	v_and_b32_e32 v3, 0xffff0000, v3
	v_fma_f32 v2, v24, v30, v5
	v_add_f32_e32 v2, v4, v2
	v_and_b32_e32 v5, 0xffff0000, v10
	v_and_b32_e32 v4, 0xffff0000, v6
	v_pk_mul_f32 v[4:5], v[20:21], v[4:5]
	s_nop 0
	v_fma_f32 v5, v24, v31, v5
	v_add_f32_e32 v4, v4, v5
	v_cvt_pk_bf16_f32 v2, v2, v4
	v_lshlrev_b32_e32 v4, 16, v7
	v_lshlrev_b32_e32 v5, 16, v11
	v_pk_mul_f32 v[4:5], v[20:21], v[4:5]
	s_nop 0
	v_fma_f32 v5, v24, v32, v5
	v_add_f32_e32 v6, v4, v5
	v_and_b32_e32 v5, 0xffff0000, v11
	v_and_b32_e32 v4, 0xffff0000, v7
	v_pk_mul_f32 v[4:5], v[20:21], v[4:5]
	s_nop 0
	v_fma_f32 v3, v24, v3, v5
	v_add_f32_e32 v3, v4, v3
	v_lshlrev_b64 v[4:5], 11, v[18:19]
	v_lshl_add_u64 v[4:5], s[84:85], 0, v[4:5]
	v_lshl_add_u64 v[4:5], v[4:5], 0, s[16:17]
	v_lshl_add_u64 v[4:5], v[4:5], 0, v[144:145]
	v_cvt_pk_bf16_f32 v3, v6, v3
	global_store_dwordx4 v[4:5], v[0:3], off offset:512
	s_nop 1
	v_or_b32_e32 v0, 16, v14
	v_ashrrev_i32_e32 v1, 31, v0
	v_lshl_add_u64 v[30:31], s[14:15], 0, v[0:1]
	v_mad_u64_u32 v[0:1], s[24:25], v30, 12, s[20:21]
	v_mad_i32_i24 v1, v31, 12, v1
	v_mad_u64_u32 v[2:3], s[24:25], v30, 12, s[18:19]
	v_lshl_add_u64 v[0:1], v[0:1], 3, s[34:35]
	v_mad_i32_i24 v3, v31, 12, v3
	v_lshl_add_u64 v[2:3], v[2:3], 3, s[34:35]
	global_load_dwordx2 v[32:33], v[0:1], off
	global_load_dwordx2 v[34:35], v[2:3], off
	v_mad_u64_u32 v[0:1], s[24:25], v30, s40, v[12:13]
	v_mad_i32_i24 v1, v31, s40, v1
	global_load_dwordx4 v[18:21], v[0:1], off
	v_mad_u64_u32 v[0:1], s[24:25], v30, s40, v[16:17]
	v_mad_i32_i24 v1, v31, s40, v1
	global_load_dwordx4 v[22:25], v[0:1], off
	v_or_b32_e32 v0, 24, v14
	v_ashrrev_i32_e32 v1, 31, v0
	v_lshl_add_u64 v[8:9], s[14:15], 0, v[0:1]
	v_mad_u64_u32 v[0:1], s[14:15], v8, 12, s[20:21]
	v_mad_i32_i24 v1, v9, 12, v1
	v_mad_u64_u32 v[2:3], s[14:15], v8, 12, s[18:19]
	v_lshl_add_u64 v[0:1], v[0:1], 3, s[34:35]
	v_mad_i32_i24 v3, v9, 12, v3
	v_lshl_add_u64 v[2:3], v[2:3], 3, s[34:35]
	global_load_dwordx2 v[10:11], v[0:1], off
	global_load_dwordx2 v[14:15], v[2:3], off
	v_mad_u64_u32 v[0:1], s[14:15], v8, s40, v[12:13]
	v_mad_i32_i24 v1, v9, s40, v1
	global_load_dwordx4 v[0:3], v[0:1], off
	v_mad_u64_u32 v[4:5], s[14:15], v8, s40, v[16:17]
	v_mad_i32_i24 v5, v9, s40, v5
	global_load_dwordx4 v[4:7], v[4:5], off
	ds_read_b128 v[26:29], v230
	ds_read2_b32 v[12:13], v210 offset0:16 offset1:48
	s_waitcnt vmcnt(6) lgkmcnt(0)
; __device__ __forceinline__ unsigned cvt_pk_bf16(float lo, float hi) { unsigned r; asm volatile("v_cvt_pk_bf16_f32 %0, %1, %2" : "=v"(r) : "v"(lo), "v"(hi)); return r; }
; #define LAS __attribute__((address_space(3)))
; template <bool MERGE> __device__ __forceinline__ void compute_b(LAS unsigned char* lds, const UD& x, unsigned char* ws, unsigned char* dout, int wid, int lane, const u32x4 (&pw)[10], float mx, float lsum) {
;     ...
; #pragma unroll
;             for (int ii = 0; ii < 2; ++ii) {
;                 const int row = (i0 + ii) * 8 + (lane >> 3), ch = lane & 7; const size_t tok = tokb + (size_t)(t0 + row);
;                 const u32x4 v0 = *(const LAS u32x4*)(stg + row * 64 + ch * 8);
;                 const float m0 = wsf[32 + row], l0 = wsf[row];
;                 const float mxx = fmaxf(fmaxf(m0, m1[ii]), m2[ii]);
;                 float w0 = __builtin_amdgcn_exp2f(m0 - mxx) * l0, w1 = __builtin_amdgcn_exp2f(m1[ii] - mxx) * l1[ii], w2 = __builtin_amdgcn_exp2f(m2[ii] - mxx) * l2[ii];
;                 const float rd = 1.0f / (w0 + w1 + w2); w0 *= rd; w1 *= rd; w2 *= rd;
;                 const u32x4 a1 = o1[ii], a2 = o2[ii];
;                 u32x4 w;
;                 w.x = pg8::cvt_pk_bf16(w0 * __uint_as_float(v0.x << 16) + w1 * __uint_as_float(a1.x << 16) + w2 * __uint_as_float(a2.x << 16), w0 * __uint_as_float(v0.x & 0xffff0000u) + w1 * __uint_as_float(a1.x & 0xffff0000u) + w2 * __uint_as_float(a2.x & 0xffff0000u));
;                 w.y = pg8::cvt_pk_bf16(w0 * __uint_as_float(v0.y << 16) + w1 * __uint_as_float(a1.y << 16) + w2 * __uint_as_float(a2.y << 16), w0 * __uint_as_float(v0.y & 0xffff0000u) + w1 * __uint_as_float(a1.y & 0xffff0000u) + w2 * __uint_as_float(a2.y & 0xffff0000u));
;                 w.z = pg8::cvt_pk_bf16(w0 * __uint_as_float(v0.z << 16) + w1 * __uint_as_float(a1.z << 16) + w2 * __uint_as_float(a2.z << 16), w0 * __uint_as_float(v0.z & 0xffff0000u) + w1 * __uint_as_float(a1.z & 0xffff0000u) + w2 * __uint_as_float(a2.z & 0xffff0000u));
;                 w.w = pg8::cvt_pk_bf16(w0 * __uint_as_float(v0.w << 16) + w1 * __uint_as_float(a1.w << 16) + w2 * __uint_as_float(a2.w << 16), w0 * __uint_as_float(v0.w & 0xffff0000u) + w1 * __uint_as_float(a1.w & 0xffff0000u) + w2 * __uint_as_float(a2.w & 0xffff0000u));
;                 *(u32x4*)(MIX + tok * DM + PWD + x.h * HD + ch * 8) = w;
;             }
;         }
;         if (x.h < 4) {
	v_max3_f32 v16, v13, v32, v34
	v_sub_f32_e32 v13, v13, v16
	v_exp_f32_e32 v17, v13
	v_sub_f32_e32 v13, v32, v16
	v_exp_f32_e32 v32, v13
	v_sub_f32_e32 v13, v34, v16
	v_exp_f32_e32 v16, v13
	s_waitcnt vmcnt(5)
	v_lshlrev_b32_e32 v34, 16, v18
	v_and_b32_e32 v37, 0xffff0000, v18
	v_lshlrev_b32_e32 v38, 16, v19
	v_and_b32_e32 v39, 0xffff0000, v19
	v_mov_b32_e32 v18, v35
	v_mov_b32_e32 v19, v12
	v_pk_mul_f32 v[12:13], v[18:19], v[16:17]
	v_mul_f32_e32 v36, v33, v32
	v_fma_f32 v16, v33, v32, v13
	v_add_f32_e32 v16, v12, v16
	v_div_scale_f32 v17, s[14:15], v16, v16, 1.0
	v_rcp_f32_e32 v18, v17
	v_lshlrev_b32_e32 v40, 16, v20
	v_and_b32_e32 v20, 0xffff0000, v20
	v_lshlrev_b32_e32 v41, 16, v21
	v_fma_f32 v19, -v17, v18, 1.0
	v_fmac_f32_e32 v18, v19, v18
	v_div_scale_f32 v19, vcc, 1.0, v16, 1.0
	v_mul_f32_e32 v32, v19, v18
	v_fma_f32 v33, -v17, v32, v19
	v_fmac_f32_e32 v32, v33, v18
	v_fma_f32 v17, -v17, v32, v19
	v_div_fmas_f32 v17, v17, v18, v32
	v_div_fixup_f32 v16, v17, v16, 1.0
	v_mul_f32_e32 v32, v36, v16
	v_pk_mul_f32 v[12:13], v[12:13], v[16:17] op_sel_hi:[1,0]
	s_waitcnt vmcnt(4)
	v_lshlrev_b32_e32 v16, 16, v22
	v_lshlrev_b32_e32 v17, 16, v26
	v_pk_mul_f32 v[16:17], v[12:13], v[16:17]
	v_lshlrev_b32_e32 v19, 16, v27
	v_fma_f32 v17, v32, v34, v17
	v_add_f32_e32 v18, v16, v17
	v_and_b32_e32 v17, 0xffff0000, v26
	v_and_b32_e32 v16, 0xffff0000, v22
	v_pk_mul_f32 v[16:17], v[12:13], v[16:17]
	s_waitcnt vmcnt(1)
	v_and_b32_e32 v26, 0xffff0000, v2
	v_fma_f32 v17, v32, v37, v17
	v_add_f32_e32 v16, v16, v17
	v_cvt_pk_bf16_f32 v16, v18, v16
	v_lshlrev_b32_e32 v18, 16, v23
	v_pk_mul_f32 v[18:19], v[12:13], v[18:19]
	s_nop 0
	v_fma_f32 v17, v32, v38, v19
	v_add_f32_e32 v17, v18, v17
	v_and_b32_e32 v19, 0xffff0000, v27
	v_and_b32_e32 v18, 0xffff0000, v23
	v_pk_mul_f32 v[18:19], v[12:13], v[18:19]
	v_lshlrev_b32_e32 v23, 16, v29
	v_fma_f32 v19, v32, v39, v19
	v_add_f32_e32 v18, v18, v19
	v_cvt_pk_bf16_f32 v17, v17, v18
	v_lshlrev_b32_e32 v18, 16, v24
	v_lshlrev_b32_e32 v19, 16, v28
	v_pk_mul_f32 v[18:19], v[12:13], v[18:19]
	v_lshlrev_b32_e32 v27, 16, v3
	v_fma_f32 v19, v32, v40, v19
	v_add_f32_e32 v22, v18, v19
	v_and_b32_e32 v19, 0xffff0000, v28
	v_and_b32_e32 v18, 0xffff0000, v24
	v_pk_mul_f32 v[18:19], v[12:13], v[18:19]
	v_and_b32_e32 v24, 0xffff0000, v1
	v_fma_f32 v19, v32, v20, v19
	v_add_f32_e32 v18, v18, v19
	v_cvt_pk_bf16_f32 v18, v22, v18
	v_lshlrev_b32_e32 v22, 16, v25
	v_pk_mul_f32 v[22:23], v[12:13], v[22:23]
	v_and_b32_e32 v20, 0xffff0000, v25
	v_fma_f32 v19, v32, v41, v23
	v_add_f32_e32 v19, v22, v19
	v_and_b32_e32 v22, 0xffff0000, v21
	v_and_b32_e32 v21, 0xffff0000, v29
	v_pk_mul_f32 v[12:13], v[12:13], v[20:21]
	v_lshlrev_b32_e32 v23, 16, v1
	v_fma_f32 v13, v32, v22, v13
	v_add_f32_e32 v12, v12, v13
	v_cvt_pk_bf16_f32 v19, v19, v12
	v_lshlrev_b64 v[12:13], 11, v[30:31]
	v_lshl_add_u64 v[12:13], s[84:85], 0, v[12:13]
	v_lshl_add_u64 v[12:13], v[12:13], 0, s[16:17]
	v_lshl_add_u64 v[12:13], v[12:13], 0, v[144:145]
	global_store_dwordx4 v[12:13], v[16:19], off offset:512
	ds_read_b128 v[16:19], v231
	ds_read2_b32 v[12:13], v210 offset0:24 offset1:56
	v_and_b32_e32 v22, 0xffff0000, v0
	v_lshlrev_b32_e32 v25, 16, v2
	s_waitcnt lgkmcnt(0)
	v_max3_f32 v20, v13, v10, v14
	v_sub_f32_e32 v13, v13, v20
	v_sub_f32_e32 v14, v14, v20
	v_exp_f32_e32 v21, v13
	v_sub_f32_e32 v10, v10, v20
	v_exp_f32_e32 v20, v14
	v_exp_f32_e32 v10, v10
	v_lshlrev_b32_e32 v14, 16, v0
	v_mov_b32_e32 v0, v15
	v_mov_b32_e32 v1, v12
	v_pk_mul_f32 v[0:1], v[0:1], v[20:21]
	v_mul_f32_e32 v13, v11, v10
	v_fma_f32 v2, v11, v10, v1
	v_add_f32_e32 v2, v0, v2
	v_div_scale_f32 v10, s[14:15], v2, v2, 1.0
	v_rcp_f32_e32 v11, v10
	s_nop 0
	v_fma_f32 v12, -v10, v11, 1.0
	v_fmac_f32_e32 v11, v12, v11
	v_div_scale_f32 v12, vcc, 1.0, v2, 1.0
	v_mul_f32_e32 v15, v12, v11
	v_fma_f32 v20, -v10, v15, v12
	v_fmac_f32_e32 v15, v20, v11
	v_fma_f32 v10, -v10, v15, v12
	v_div_fmas_f32 v10, v10, v11, v15
	v_div_fixup_f32 v2, v10, v2, 1.0
	v_pk_mul_f32 v[10:11], v[0:1], v[2:3] op_sel_hi:[1,0]
	s_waitcnt vmcnt(1)
	v_lshlrev_b32_e32 v0, 16, v4
	v_lshlrev_b32_e32 v1, 16, v16
	v_mul_f32_e32 v15, v13, v2
	v_pk_mul_f32 v[0:1], v[10:11], v[0:1]
	v_lshlrev_b32_e32 v12, 16, v5
	v_fma_f32 v1, v15, v14, v1
	v_add_f32_e32 v2, v0, v1
	v_and_b32_e32 v1, 0xffff0000, v16
	v_and_b32_e32 v0, 0xffff0000, v4
	v_pk_mul_f32 v[0:1], v[10:11], v[0:1]
	v_lshlrev_b32_e32 v13, 16, v17
	v_fma_f32 v1, v15, v22, v1
	v_pk_mul_f32 v[12:13], v[10:11], v[12:13]
	v_add_f32_e32 v0, v0, v1
	v_fma_f32 v1, v15, v23, v13
	v_add_f32_e32 v1, v12, v1
	v_and_b32_e32 v13, 0xffff0000, v17
	v_and_b32_e32 v12, 0xffff0000, v5
	v_pk_mul_f32 v[4:5], v[10:11], v[12:13]
	v_cvt_pk_bf16_f32 v0, v2, v0
	v_and_b32_e32 v3, 0xffff0000, v3
	v_fma_f32 v2, v15, v24, v5
	v_add_f32_e32 v2, v4, v2
	v_lshlrev_b32_e32 v4, 16, v6
	v_lshlrev_b32_e32 v5, 16, v18
	v_pk_mul_f32 v[4:5], v[10:11], v[4:5]
	v_cvt_pk_bf16_f32 v1, v1, v2
	s_nop 0
	v_fma_f32 v2, v15, v25, v5
	v_add_f32_e32 v2, v4, v2
	v_and_b32_e32 v5, 0xffff0000, v18
	v_and_b32_e32 v4, 0xffff0000, v6
	v_pk_mul_f32 v[4:5], v[10:11], v[4:5]
	s_nop 0
	v_fma_f32 v5, v15, v26, v5
	v_add_f32_e32 v4, v4, v5
	v_cvt_pk_bf16_f32 v2, v2, v4
	v_lshlrev_b32_e32 v4, 16, v7
	v_lshlrev_b32_e32 v5, 16, v19
	v_pk_mul_f32 v[4:5], v[10:11], v[4:5]
	s_nop 0
	v_fma_f32 v5, v15, v27, v5
	v_add_f32_e32 v6, v4, v5
	v_and_b32_e32 v5, 0xffff0000, v19
	v_and_b32_e32 v4, 0xffff0000, v7
	v_pk_mul_f32 v[4:5], v[10:11], v[4:5]
	s_nop 0
	v_fma_f32 v3, v15, v3, v5
	v_add_f32_e32 v3, v4, v3
	v_lshlrev_b64 v[4:5], 11, v[8:9]
	v_lshl_add_u64 v[4:5], s[84:85], 0, v[4:5]
	v_lshl_add_u64 v[4:5], v[4:5], 0, s[16:17]
	v_lshl_add_u64 v[4:5], v[4:5], 0, v[144:145]
	v_cvt_pk_bf16_f32 v3, v6, v3
	global_store_dwordx4 v[4:5], v[0:3], off offset:512
	s_cbranch_scc1 .LBB0_902
; template <bool MERGE> __device__ __forceinline__ void compute_b(LAS unsigned char* lds, const UD& x, unsigned char* ws, unsigned char* dout, int wid, int lane, const u32x4 (&pw)[10], float mx, float lsum) {
;     ...
;         if (x.h < 4) {
;             const int g = x.h, hw = 1 << g;
;             const bf16_t* VP = (const bf16_t*)(ws + off_vp(x.b));
; #pragma unroll 1
;             for (int p = 0; p < 8; ++p) {
;                 const int s = t0 + 4 * p + (lane >> 4);
;                 const bf16_t* base = VP + tokb * PWD + g * 64 + 4 * (lane & 15);
;                 float s0 = 0.f, s1 = 0.f, s2 = 0.f, s3 = 0.f; int cnt = 0;
;                 const u32x2 me = *(const u32x2*)(base + (size_t)s * PWD);
	s_bfe_u32 s14, s45, 0x30008
	s_lshl_b32 s18, s14, 17
	s_lshl_b32 s19, s14, 8
	s_lshl_b32 s20, -1, s22
	s_mul_i32 s15, s0, 0xa00000
	v_readlane_b32 s24, v252, 1
	s_mul_hi_i32 s14, s0, 0xa00000
	v_readlane_b32 s25, v252, 2
	s_add_u32 s21, s24, s15
	s_addc_u32 s23, s25, s14
	s_lshl_b64 s[14:15], s[0:1], 20
	s_add_u32 s14, s21, s14
	s_addc_u32 s15, s23, s15
	s_add_u32 s14, s14, s16
	s_addc_u32 s15, s15, s17
	v_add_u32_e32 v0, s19, v212
	s_cmp_lg_u32 s22, 0
	v_ashrrev_i32_e32 v1, 31, v0
	v_mov_b32_e32 v147, v81
	s_cselect_b64 s[46:47], -1, 0
	s_cmp_gt_u32 s22, 1
	v_lshlrev_b64 v[4:5], 11, v[0:1]
	v_lshlrev_b64 v[6:7], 9, v[0:1]
	v_lshl_add_u64 v[0:1], s[14:15], 0, v[146:147]
	s_mov_b64 s[14:15], 0xc400000
	s_cselect_b64 s[54:55], -1, 0
	s_cmp_gt_u32 s22, 2
	v_lshl_add_u64 v[0:1], v[0:1], 0, s[14:15]
	s_cselect_b64 s[56:57], -1, 0
	s_lshl_b32 s14, s20, 9
	s_add_i32 s14, s14, s18
	v_add_u32_e32 v2, s14, v211
	s_add_i32 s19, s19, s20
	s_lshl_b64 s[14:15], s[0:1], 22
	s_add_u32 s14, s16, s14
	s_addc_u32 s15, s17, s15
	s_mul_hi_i32 s1, s0, 0xb00000
	s_mul_i32 s0, s0, 0xb00000
	s_add_u32 s0, s16, s0
	s_addc_u32 s1, s17, s1
	v_lshl_add_u64 v[4:5], s[14:15], 0, v[4:5]
	v_lshl_add_u64 v[6:7], s[0:1], 0, v[6:7]
	v_add_u32_e32 v3, s19, v213
	v_lshl_add_u64 v[4:5], v[138:139], 0, v[4:5]
	v_lshl_add_u64 v[6:7], v[140:141], 0, v[6:7]
	s_mov_b64 s[58:59], 0
	v_mbcnt_lo_u32_b32 v232, -1, 0
	v_mbcnt_hi_u32_b32 v232, -1, v232
	v_lshrrev_b32_e32 v233, 3, v232
	v_lshrrev_b32_e32 v234, 4, v232
	v_sub_u32_e32 v233, v233, v234
	v_and_b32_e32 v234, 7, v232
	v_and_b32_e32 v235, 15, v232
	v_lshlrev_b32_e32 v234, 4, v234
	v_lshlrev_b32_e32 v235, 3, v235
	v_sub_u32_e32 v234, v234, v235
	v_lshl_add_u32 v235, v233, 9, v234
	v_lshl_add_u32 v233, v233, 11, v234
	v_ashrrev_i32_e32 v234, 31, v235
	v_add_co_u32_e32 v76, vcc, v6, v235
	v_addc_co_u32_e32 v77, vcc, v7, v234, vcc
	v_ashrrev_i32_e32 v234, 31, v233
	v_add_co_u32_e32 v78, vcc, v4, v233
	v_addc_co_u32_e32 v79, vcc, v5, v234, vcc
	v_readfirstlane_b32 s98, v3
	s_sub_i32 s98, s98, s20
	s_add_i32 s98, s98, -15
	s_mov_b32 s99, 0
	s_mov_b32 s100, 4
	s_mov_b32 s101, 0
	s_cmp_eq_u32 s98, 0
	s_cbranch_scc0 .Lpl_chk_hi
	s_mov_b32 s99, 1
	s_movk_i32 s101, 0x1000
	s_branch .LBB0_944
